# attention phase: static s_setprio 1 for waves 0-3 instead (mirror of v35)
# baseline (speedup 1.0000x reference)
.LBB0_667:
	v_writelane_b32 v255, s94, 2
	v_writelane_b32 v254, s72, 50
	s_andn2_b64 vcc, exec, s[8:9]
	v_writelane_b32 v255, s95, 3
	v_writelane_b32 v254, s73, 51
	v_writelane_b32 v255, s62, 4
	v_writelane_b32 v254, s74, 52
	v_writelane_b32 v254, s75, 53
	v_writelane_b32 v255, s63, 5
	s_cbranch_vccnz .LBB0_736
	s_bfe_u32 s4, s34, 0x30002
	s_add_i32 s5, s4, 1
	v_cvt_f32_ubyte0_e32 v0, s5
	s_mov_b32 s5, 0x42fc0000
	s_waitcnt vmcnt(0)
	v_ashrrev_i32_e32 v5, 6, v166
	v_and_b32_e32 v107, 15, v166
	s_ashr_i32 s8, s34, 5
	v_cmp_lt_f32_e32 vcc, s5, v0
	v_mov_b32_e32 v2, 0x42800000
	s_and_b32 s20, s34, 3
	s_ashr_i32 s9, s8, 31
	v_cndmask_b32_e32 v2, 0, v2, vcc
	v_lshl_or_b32 v109, v5, 4, v107
	s_lshl_b64 s[18:19], s[8:9], 12
	v_sub_f32_e32 v0, v2, v0
	v_lshl_add_u32 v2, s20, 10, v109
	v_exp_f32_e32 v0, v0
	s_and_b64 s[8:9], vcc, exec
	v_ashrrev_i32_e32 v3, 31, v2
	v_lshl_add_u64 v[2:3], s[18:19], 0, v[2:3]
	v_readlane_b32 s8, v253, 53
	v_lshlrev_b64 v[2:3], 11, v[2:3]
	v_readlane_b32 s9, v253, 54
	v_bfe_u32 v6, v166, 4, 2
	s_cselect_b32 s5, 0xffffffc0, 0
	v_lshl_add_u64 v[2:3], s[8:9], 0, v[2:3]
	s_lshl_b32 s6, s4, 8
	v_ldexp_f32 v7, v0, s5
	v_lshl_add_u64 v[2:3], v[2:3], 0, s[6:7]
	v_lshlrev_b32_e32 v0, 4, v6
	v_lshl_add_u64 v[2:3], v[2:3], 0, v[0:1]
	global_load_dwordx4 v[62:65], v[2:3], off
	global_load_dwordx4 v[58:61], v[2:3], off offset:64
	global_load_dwordx4 v[54:57], v[2:3], off offset:128
	global_load_dwordx4 v[50:53], v[2:3], off offset:192
	v_and_b32_e32 v3, 1, v5
	v_cmp_eq_u32_e64 s[8:9], 0, v3
	s_lshl_b32 s6, s20, 3
	v_writelane_b32 v255, s6, 6
	v_writelane_b32 v254, s8, 54
	v_and_b32_e32 v14, 64, v224
	v_writelane_b32 v255, s20, 7
	v_writelane_b32 v254, s9, 55
	v_cmp_eq_u32_e64 s[8:9], 1, v3
	v_xor_b32_e32 v13, 16, v224
	v_add_u32_e32 v14, 64, v14
	v_writelane_b32 v254, s8, 62
	v_and_b32_e32 v111, -2, v5
	v_cmp_lt_i32_e32 vcc, v13, v14
	v_writelane_b32 v254, s9, 63
	s_lshl_b32 s8, s20, 2
	v_writelane_b32 v255, s8, 8
	v_cmp_eq_u32_e64 s[8:9], 0, v6
	v_add_u32_e32 v106, 0, v0
	v_lshl_or_b32 v0, v3, 4, v107
	v_writelane_b32 v254, s8, 60
	v_cndmask_b32_e32 v13, v224, v13, vcc
	v_or_b32_e32 v3, 0x80, v0
	v_writelane_b32 v254, s9, 61
	v_cmp_lt_i32_e64 s[8:9], 7, v111
	v_lshlrev_b32_e32 v8, 2, v6
	v_lshlrev_b32_e32 v116, 2, v13
	v_xor_b32_e32 v13, 32, v224
	v_writelane_b32 v254, s8, 56
	v_sub_u32_e32 v9, v3, v8
	v_cmp_lt_i32_e32 vcc, v13, v14
	v_lshlrev_b32_e32 v14, 4, v166
	v_writelane_b32 v254, s9, 57
	s_movk_i32 s8, 0x81
	v_lshlrev_b32_e32 v4, 3, v6
	v_and_b32_e32 v15, 48, v14
	v_readlane_b32 s6, v253, 20
	v_and_b32_e32 v14, 0xf0, v14
	v_subrev_co_u32_e64 v6, s[20:21], s8, v9
	v_add_u32_e32 v108, s6, v15
	v_add_u32_e32 v123, s6, v14
	v_writelane_b32 v254, s20, 58
	v_sub_u32_e32 v3, v8, v3
	s_movk_i32 s6, 0xff7e
	v_writelane_b32 v254, s21, 59
	v_cmp_lt_u32_e64 s[20:21], s6, v3
	v_add_u32_e32 v3, -2, v9
	v_mul_f32_e32 v2, 0x3fb8aa3b, v7
	v_writelane_b32 v255, s20, 9
	v_cvt_f32_ubyte0_e32 v10, v9
	v_mul_f32_e32 v11, 0x41800000, v2
	v_writelane_b32 v255, s21, 10
	v_cmp_gt_u32_e64 s[20:21], s8, v3
	v_add_u32_e32 v3, -3, v9
	v_mul_f32_e32 v12, v2, v10
	v_writelane_b32 v255, s20, 11
	s_mov_b32 s6, 0x40400000
	v_sub_u32_e32 v0, v0, v8
	v_writelane_b32 v255, s21, 12
	v_cmp_gt_u32_e64 s[20:21], s8, v3
	v_fma_f32 v145, v11, s6, -v12
	s_mov_b32 s6, 0x40a00000
	v_writelane_b32 v255, s20, 13
	v_lshlrev_b32_e32 v15, 3, v166
	v_fma_f32 v153, v11, s6, -v12
	v_writelane_b32 v255, s21, 14
	v_cmp_gt_u32_e64 s[20:21], s8, v0
	v_add_u32_e32 v0, 0xffffff7e, v9
	s_mov_b32 s6, 0x40c00000
	v_cmp_gt_u32_e64 s[42:43], s8, v0
	v_add_u32_e32 v0, 0xffffff7d, v9
	s_lshl_b32 s5, s4, 7
	v_and_b32_e32 v15, 0x78, v15
	v_add_u32_e32 v3, -16, v9
	v_fma_f32 v157, v11, s6, -v12
	s_mov_b32 s6, 0x40e00000
	v_cmp_gt_u32_e64 s[44:45], s8, v0
	v_add_u32_e32 v0, 0xffffff70, v9
	v_or_b32_e32 v110, s5, v15
	v_add_u32_e32 v15, 0x200, v166
	v_cmp_gt_u32_e64 s[58:59], s8, v3
	v_subrev_u32_e32 v3, 17, v9
	v_fma_f32 v161, v11, s6, -v12
	s_mov_b32 s6, 0x41000000
	v_cmp_gt_u32_e64 s[48:49], s8, v0
	v_add_u32_e32 v0, 0xffffff6f, v9
	v_cndmask_b32_e32 v13, v224, v13, vcc
	v_ashrrev_i32_e32 v119, 4, v15
	v_add_u32_e32 v15, 0x400, v166
	v_cmp_gt_u32_e64 s[60:61], s8, v3
	v_subrev_u32_e32 v3, 18, v9
	v_fma_f32 v169, v11, s6, -v12
	s_mov_b32 s6, 0x41100000
	v_cmp_gt_u32_e64 s[50:51], s8, v0
	v_add_u32_e32 v0, 0xffffff6e, v9
	v_lshlrev_b32_e32 v117, 2, v13
	v_bfe_u32 v13, v166, 2, 2
	v_ashrrev_i32_e32 v120, 4, v15
	v_add_u32_e32 v15, 0x600, v166
	v_fma_f32 v133, v11, 0, -v12
	v_fma_f32 v137, -v2, v10, v11
	v_cmp_gt_u32_e64 s[62:63], s8, v3
	v_subrev_u32_e32 v3, 19, v9
	v_fma_f32 v141, v11, 2.0, -v12
	v_fma_f32 v149, v11, 4.0, -v12
	v_fma_f32 v173, v11, s6, -v12
	v_cmp_gt_u32_e64 s[90:91], s8, v0
	v_add_u32_e32 v0, 0xffffff6d, v9
	s_mov_b32 s53, 0
	v_ashrrev_i32_e32 v118, 4, v166
	v_ashrrev_i32_e32 v121, 4, v15
	v_add_u32_e32 v122, 0, v14
	v_or_b32_e32 v124, 1, v5
	v_add_u32_e32 v125, 2, v111
	v_add_u32_e32 v126, 3, v111
	v_add_u32_e32 v127, 4, v111
	v_add_u32_e32 v128, 5, v111
	v_add_u32_e32 v129, 6, v111
	v_add_u32_e32 v130, 7, v111
	v_add_u32_e32 v131, 8, v111
	v_add_u32_e32 v132, 9, v111
	v_fma_f32 v134, 0, v2, v133
	v_fmamk_f32 v135, v7, 0x3fb8aa3b, v133
	v_fma_f32 v136, 2.0, v2, v133
	v_fmac_f32_e32 v133, 0x40400000, v2
	v_cmp_lt_i32_e64 s[56:57], 6, v111
	v_fma_f32 v138, 0, v2, v137
	v_fmamk_f32 v139, v7, 0x3fb8aa3b, v137
	v_fma_f32 v140, 2.0, v2, v137
	v_fmac_f32_e32 v137, 0x40400000, v2
	v_cmp_gt_u32_e64 s[46:47], s8, v3
	v_cmp_lt_i32_e64 s[66:67], 5, v111
	v_fma_f32 v142, 0, v2, v141
	v_fmamk_f32 v143, v7, 0x3fb8aa3b, v141
	v_fma_f32 v144, 2.0, v2, v141
	v_fmac_f32_e32 v141, 0x40400000, v2
	v_cmp_lt_i32_e64 s[68:69], 4, v111
	v_fma_f32 v146, 0, v2, v145
	v_fmamk_f32 v147, v7, 0x3fb8aa3b, v145
	v_fma_f32 v148, 2.0, v2, v145
	v_fmac_f32_e32 v145, 0x40400000, v2
	v_cmp_lt_i32_e64 s[70:71], 3, v111
	v_fma_f32 v150, 0, v2, v149
	v_fmamk_f32 v151, v7, 0x3fb8aa3b, v149
	v_fma_f32 v152, 2.0, v2, v149
	v_fmac_f32_e32 v149, 0x40400000, v2
	v_cmp_lt_i32_e64 s[72:73], 2, v111
	v_fma_f32 v154, 0, v2, v153
	v_fmamk_f32 v155, v7, 0x3fb8aa3b, v153
	v_fma_f32 v156, 2.0, v2, v153
	v_fmac_f32_e32 v153, 0x40400000, v2
	v_cmp_lt_i32_e64 s[74:75], 1, v5
	v_fma_f32 v158, 0, v2, v157
	v_fmamk_f32 v159, v7, 0x3fb8aa3b, v157
	v_fma_f32 v160, 2.0, v2, v157
	v_fmac_f32_e32 v157, 0x40400000, v2
	v_fma_f32 v162, 0, v2, v161
	v_fmamk_f32 v167, v7, 0x3fb8aa3b, v161
	v_fma_f32 v168, 2.0, v2, v161
	v_fmac_f32_e32 v161, 0x40400000, v2
	v_cmp_lt_i32_e64 s[76:77], -1, v5
	v_fma_f32 v170, 0, v2, v169
	v_fmamk_f32 v171, v7, 0x3fb8aa3b, v169
	v_cmp_gt_u32_e64 s[40:41], s8, v6
	v_fma_f32 v172, 2.0, v2, v169
	v_fmac_f32_e32 v169, 0x40400000, v2
	v_fma_f32 v174, 0, v2, v173
	v_fmamk_f32 v175, v7, 0x3fb8aa3b, v173
	v_fma_f32 v176, 2.0, v2, v173
	v_cmp_gt_u32_e64 s[92:93], s8, v0
	v_fmac_f32_e32 v173, 0x40400000, v2
	v_or_b32_e32 v177, v8, v13
	v_lshlrev_b32_e32 v0, 1, v4
	s_lshl_b32 s38, s4, 2
	v_readfirstlane_b32 s100, v220
	s_nop 3
	s_lshr_b32 s100, s100, 6
	s_cmp_lt_u32 s100, 4
	s_cbranch_scc0 .Lattn_prio_done
	s_setprio 1
